# nt (streaming) hint on P6 epilogue ACT stores only, on top of pipelined P2c/P2d
# speedup vs baseline: 1.0012x; 1.0012x over previous
;     __device__ __forceinline__ void operator()(EPI_ARGS) const {
;         const int f0 = u.pn * 128 + wc * 32 + 8 * fq;
;         const int lane = fq * 16 + fr, src1 = (lane & 48) | ((fr - 1) & 15), src2 = (lane & 48) | ((fr - 2) & 15);
;         f32x4 w0[2], w1[2], w2[2], bb[2];
; #pragma unroll
;         for (int n = 0; n < 2; ++n) { w0[n] = *(const f32x4*)(cw + f0 + 4 * n); w1[n] = *(const f32x4*)(cw + FF + f0 + 4 * n); w2[n] = *(const f32x4*)(cw + 2 * FF + f0 + 4 * n); bb[n] = *(const f32x4*)(cb + f0 + 4 * n); }
;         float rsv[2][4];
; #pragma unroll
;         for (int ai = 0; ai < 2; ++ai)
; #pragma unroll
;             for (int m = 0; m < 4; ++m) rsv[ai][m] = ss2[ROW_OF(ai, m)];
; #pragma unroll
;         for (int ai = 0; ai < 2; ++ai) {
;             const int blk = u.pm * 4 + ai * 2 + wr;
;             f32x4 q1[2], q2[2];
; #pragma unroll
;             for (int n = 0; n < 2; ++n) { q1[n] = (f32x4){0.f, 0.f, 0.f, 0.f}; q2[n] = (f32x4){0.f, 0.f, 0.f, 0.f}; }
; #pragma unroll
;             for (int m = 0; m < 4; ++m) {
;                 const int row = ROW_OF(ai, m);
;                 const float rs = __builtin_amdgcn_rsqf(rsv[ai][m] * (1.0f / D) + EPS);
;                 f32x4 o[2];
; #pragma unroll
;                 for (int n = 0; n < 2; ++n) {
;                     const f32x4 gv = acc[ai][0][m][n] * rs, vv = acc[ai][1][m][n] * rs;
;                     f32x4 r1, r2;
; #pragma unroll
;                     for (int j = 0; j < 4; ++j) { r1[j] = __shfl(gv[j], src1); r2[j] = __shfl(gv[j], src2); }
;                     f32x4 p1, p2;
; #pragma unroll
;                     for (int j = 0; j < 4; ++j) { p1[j] = fr >= 1 ? r1[j] : q1[n][j]; p2[j] = fr >= 2 ? r2[j] : q2[n][j]; }
;                     q1[n] = r1; q2[n] = r2;
;                     const f32x4 cv = bb[n] + w0[n] * p2 + w1[n] * p1 + w2[n] * gv;
;                     o[n] = gelu4(cv) * vv;
;                     if (m == 0 && fr < 2) { const size_t so = ((size_t)blk * 2 + fr) * FF + f0 + 4 * n; *(f32x4*)(headg + so) = gv; *(f32x4*)(headv + so) = vv; }
;                     if (m == 3 && fr >= 14) { const size_t so = ((size_t)blk * 2 + (fr - 14)) * FF + f0 + 4 * n; *(f32x4*)(tailg + so) = gv; }
.LBB0_926:
	s_lshl_b32 s0, s9, 7
	v_mov_b32_e32 v184, v206
	v_mov_b32_e32 v168, v207
	s_or_b32 s0, s0, s35
	s_nop 0
	v_lshl_add_u32 v174, v168, 3, s0
	s_lshl_b32 s0, s8, 8
	s_add_i32 s0, s0, s34
	v_ashrrev_i32_e32 v175, 31, v174
	v_add_u32_e32 v192, s0, v184
	v_lshlrev_b64 v[64:65], 2, v[174:175]
	v_ashrrev_i32_e32 v193, 31, v192
	v_lshl_add_u64 v[66:67], s[84:85], 0, v[64:65]
	v_lshl_add_u64 v[68:69], s[16:17], 0, v[64:65]
	v_lshl_add_u64 v[70:71], s[18:19], 0, v[64:65]
	v_lshl_add_u64 v[76:77], s[86:87], 0, v[64:65]
	v_lshl_add_u64 v[176:177], v[192:193], 2, s[68:69]
	global_load_dwordx4 v[92:95], v[66:67], off offset:16
	global_load_dwordx4 v[72:75], v[66:67], off
	global_load_dwordx4 v[84:87], v[68:69], off offset:16
	s_nop 0
	global_load_dwordx4 v[64:67], v[68:69], off
	global_load_dwordx4 v[88:91], v[70:71], off offset:16
	s_nop 0
	global_load_dwordx4 v[68:71], v[70:71], off
	s_nop 0
	global_load_dwordx4 v[96:99], v[76:77], off offset:16
	s_nop 0
	global_load_dwordx4 v[76:79], v[76:77], off
	v_add_u32_e32 v190, 16, v192
	global_load_dword v220, v[176:177], off
	v_ashrrev_i32_e32 v191, 31, v190
	v_add_u32_e32 v188, 32, v192
	v_add_u32_e32 v186, 48, v192
	v_add_u32_e32 v182, 0x80, v192
	v_add_u32_e32 v180, 0x90, v192
	v_add_u32_e32 v178, 0xa0, v192
	v_add_u32_e32 v176, 0xb0, v192
	v_lshl_add_u64 v[194:195], v[190:191], 2, s[68:69]
	v_ashrrev_i32_e32 v189, 31, v188
	v_ashrrev_i32_e32 v187, 31, v186
	v_ashrrev_i32_e32 v183, 31, v182
	v_ashrrev_i32_e32 v181, 31, v180
	v_ashrrev_i32_e32 v179, 31, v178
	v_ashrrev_i32_e32 v177, 31, v176
	v_lshl_add_u64 v[196:197], v[188:189], 2, s[68:69]
	v_lshl_add_u64 v[198:199], v[186:187], 2, s[68:69]
	v_lshl_add_u64 v[200:201], v[182:183], 2, s[68:69]
	v_lshl_add_u64 v[202:203], v[180:181], 2, s[68:69]
	v_lshl_add_u64 v[204:205], v[178:179], 2, s[68:69]
	v_lshl_add_u64 v[218:219], v[176:177], 2, s[68:69]
	global_load_dword v217, v[194:195], off
	global_load_dword v193, v[196:197], off
	global_load_dword v191, v[198:199], off
	global_load_dword v189, v[200:201], off
	global_load_dword v187, v[202:203], off
	global_load_dword v183, v[204:205], off
	global_load_dword v181, v[218:219], off
	v_lshl_add_u32 v168, v168, 4, v184
	v_add_u32_e32 v177, -1, v184
	v_add_u32_e32 v179, 14, v184
	v_and_b32_e32 v177, 15, v177
	v_and_b32_e32 v179, 15, v179
	v_and_b32_e32 v168, 48, v168
	v_or3_b32 v177, v168, v177, v214
	v_or3_b32 v168, v168, v179, v214
	s_lshl_b32 s0, s8, 2
	s_add_i32 s60, s0, s29
	s_ashr_i32 s61, s60, 31
	v_lshlrev_b32_e32 v177, 2, v177
	v_ashrrev_i32_e32 v185, 31, v184
	s_lshl_b64 s[62:63], s[60:61], 1
	v_lshl_add_u64 v[194:195], s[62:63], 0, v[184:185]
	v_mad_u64_u32 v[196:197], s[0:1], v194, s65, v[174:175]
	v_mad_i32_i24 v197, v195, s65, v197
	v_cmp_lt_i32_e64 s[6:7], 1, v184
	v_cmp_gt_i32_e64 s[8:9], 2, v184
	v_lshlrev_b64 v[202:203], 2, v[196:197]
	s_waitcnt vmcnt(0)
	v_fmamk_f32 v179, v220, 0x3a000000, v215
	v_rsq_f32_e32 v204, v179
	v_lshlrev_b32_e32 v179, 2, v168
	v_pk_mul_f32 v[158:159], v[158:159], v[204:205] op_sel_hi:[1,0]
	v_pk_mul_f32 v[156:157], v[156:157], v[204:205] op_sel_hi:[1,0]
	ds_bpermute_b32 v218, v177, v156
	ds_bpermute_b32 v219, v179, v156
	ds_bpermute_b32 v220, v177, v157
	ds_bpermute_b32 v221, v179, v157
	ds_bpermute_b32 v222, v177, v158
	ds_bpermute_b32 v223, v179, v158
	ds_bpermute_b32 v224, v177, v159
	ds_bpermute_b32 v225, v179, v159
	v_pk_mul_f32 v[154:155], v[154:155], v[204:205] op_sel_hi:[1,0]
	v_pk_mul_f32 v[152:153], v[152:153], v[204:205] op_sel_hi:[1,0]
	s_and_saveexec_b64 s[0:1], s[8:9]
	s_cbranch_execz .LBB0_928
	v_lshl_add_u64 v[196:197], s[24:25], 0, v[202:203]
	v_lshl_add_u64 v[194:195], s[38:39], 0, v[202:203]
	global_store_dwordx4 v[196:197], v[156:159], off nt
	global_store_dwordx4 v[194:195], v[152:155], off nt
.LBB0_928:
	s_or_b64 exec, exec, s[0:1]
	v_mov_b32_e32 v205, v204
	v_mov_b32_e32 v226, v204
	v_mov_b32_e32 v227, v204
	v_pk_mul_f32 v[150:151], v[150:151], v[226:227]
	v_pk_mul_f32 v[148:149], v[148:149], v[204:205]
	ds_bpermute_b32 v194, v177, v148
	ds_bpermute_b32 v198, v179, v148
	ds_bpermute_b32 v195, v177, v149
	ds_bpermute_b32 v199, v179, v149
	ds_bpermute_b32 v196, v177, v150
	ds_bpermute_b32 v200, v179, v150
	ds_bpermute_b32 v197, v177, v151
	ds_bpermute_b32 v201, v179, v151
	v_cmp_lt_i32_e32 vcc, 0, v184
	v_cmp_lt_i32_e64 s[0:1], 1, v184
	v_pk_mul_f32 v[146:147], v[146:147], v[226:227]
	v_pk_mul_f32 v[144:145], v[144:145], v[204:205]
	s_and_saveexec_b64 s[4:5], s[6:7]
	s_xor_b64 s[4:5], exec, s[4:5]
	s_cbranch_execz .LBB0_930
; __device__ __forceinline__ unsigned cvt_pk_bf16(float lo, float hi) { unsigned r; asm volatile("v_cvt_pk_bf16_f32 %0, %1, %2" : "=v"(r) : "v"(lo), "v"(hi)); return r; }
;     __device__ __forceinline__ void operator()(EPI_ARGS) const {
;     ...
;                 for (int n = 0; n < 2; ++n) {
;                     const f32x4 gv = acc[ai][0][m][n] * rs, vv = acc[ai][1][m][n] * rs;
;                     f32x4 r1, r2;
; #pragma unroll
;                     for (int j = 0; j < 4; ++j) { r1[j] = __shfl(gv[j], src1); r2[j] = __shfl(gv[j], src2); }
;                     f32x4 p1, p2;
; #pragma unroll
;                     for (int j = 0; j < 4; ++j) { p1[j] = fr >= 1 ? r1[j] : q1[n][j]; p2[j] = fr >= 2 ? r2[j] : q2[n][j]; }
;                     q1[n] = r1; q2[n] = r2;
;                     const f32x4 cv = bb[n] + w0[n] * p2 + w1[n] * p1 + w2[n] * gv;
;                     o[n] = gelu4(cv) * vv;
;                     if (m == 0 && fr < 2) { const size_t so = ((size_t)blk * 2 + fr) * FF + f0 + 4 * n; *(f32x4*)(headg + so) = gv; *(f32x4*)(headv + so) = vv; }
;                     if (m == 3 && fr >= 14) { const size_t so = ((size_t)blk * 2 + (fr - 14)) * FF + f0 + 4 * n; *(f32x4*)(tailg + so) = gv; }
;                 }
;                 if (!(m == 0 && fr < 2)) {
;                     u32x4 w; w.x = cvt_pk_bf16(o[0][0], o[0][1]); w.y = cvt_pk_bf16(o[0][2], o[0][3]); w.z = cvt_pk_bf16(o[1][0], o[1][1]); w.w = cvt_pk_bf16(o[1][2], o[1][3]);
;                     *(u32x4*)(act + (size_t)row * FF + f0) = w;
	s_waitcnt lgkmcnt(14)
	v_cndmask_b32_e64 v204, 0, v219, s[0:1]
	s_waitcnt lgkmcnt(12)
	v_cndmask_b32_e64 v205, 0, v221, s[0:1]
	v_cndmask_b32_e32 v202, 0, v218, vcc
	v_cndmask_b32_e32 v203, 0, v220, vcc
	s_waitcnt lgkmcnt(10)
	v_cndmask_b32_e64 v228, 0, v223, s[0:1]
	s_waitcnt lgkmcnt(8)
	v_cndmask_b32_e64 v229, 0, v225, s[0:1]
	v_pk_fma_f32 v[204:205], v[72:73], v[204:205], v[76:77]
	v_cndmask_b32_e32 v226, 0, v222, vcc
	v_cndmask_b32_e32 v227, 0, v224, vcc
	v_pk_fma_f32 v[228:229], v[74:75], v[228:229], v[78:79]
	v_pk_fma_f32 v[202:203], v[64:65], v[202:203], v[204:205]
	v_pk_fma_f32 v[226:227], v[66:67], v[226:227], v[228:229]
	v_pk_fma_f32 v[156:157], v[68:69], v[156:157], v[202:203]
	v_pk_fma_f32 v[158:159], v[70:71], v[158:159], v[226:227]
	v_pk_mul_f32 v[204:205], v[156:157], v[156:157]
	v_pk_mul_f32 v[202:203], v[158:159], v[158:159]
	v_fmamk_f32 v168, v204, 0xbdd2d3e8, v216
	v_mul_f32_e32 v168, v156, v168
	v_fmamk_f32 v204, v205, 0xbdd2d3e8, v216
	v_fmamk_f32 v202, v202, 0xbdd2d3e8, v216
	v_exp_f32_e32 v168, v168
	v_mul_f32_e32 v204, v157, v204
	v_mul_f32_e32 v202, v158, v202
	v_exp_f32_e32 v204, v204
	v_exp_f32_e32 v205, v202
	v_fmamk_f32 v202, v203, 0xbdd2d3e8, v216
	v_mul_f32_e32 v202, v159, v202
	v_exp_f32_e32 v226, v202
	v_add_f32_e32 v168, 1.0, v168
	v_rcp_f32_e32 v202, v168
	v_add_f32_e32 v168, 1.0, v204
	v_rcp_f32_e32 v203, v168
	v_add_f32_e32 v168, 1.0, v205
	v_rcp_f32_e32 v204, v168
	v_add_f32_e32 v168, 1.0, v226
	v_rcp_f32_e32 v205, v168
	v_pk_mul_f32 v[156:157], v[156:157], v[202:203]
	s_waitcnt lgkmcnt(0)
	v_pk_fma_f32 v[202:203], v[94:95], v[200:201], v[98:99]
	v_pk_mul_f32 v[152:153], v[152:153], v[156:157]
	v_pk_mul_f32 v[158:159], v[158:159], v[204:205]
	v_pk_fma_f32 v[204:205], v[92:93], v[198:199], v[96:97]
	v_pk_fma_f32 v[202:203], v[86:87], v[196:197], v[202:203]
	v_pk_fma_f32 v[204:205], v[84:85], v[194:195], v[204:205]
	v_pk_fma_f32 v[150:151], v[90:91], v[150:151], v[202:203]
	v_pk_fma_f32 v[148:149], v[88:89], v[148:149], v[204:205]
	v_pk_mul_f32 v[202:203], v[150:151], v[150:151]
	v_pk_mul_f32 v[204:205], v[148:149], v[148:149]
	v_fmamk_f32 v202, v202, 0xbdd2d3e8, v216
	v_fmamk_f32 v168, v204, 0xbdd2d3e8, v216
	v_mul_f32_e32 v168, v148, v168
	v_exp_f32_e32 v168, v168
	v_fmamk_f32 v203, v203, 0xbdd2d3e8, v216
	v_mul_f32_e32 v202, v150, v202
	v_mul_f32_e32 v203, v151, v203
	v_add_f32_e32 v168, 1.0, v168
	v_rcp_f32_e32 v204, v168
	v_fmamk_f32 v168, v205, 0xbdd2d3e8, v216
	v_mul_f32_e32 v168, v149, v168
	v_exp_f32_e32 v168, v168
	v_exp_f32_e32 v202, v202
	v_exp_f32_e32 v203, v203
	v_pk_mul_f32 v[154:155], v[154:155], v[158:159]
	v_add_f32_e32 v168, 1.0, v168
	v_add_f32_e32 v202, 1.0, v202
	v_add_f32_e32 v203, 1.0, v203
	v_rcp_f32_e32 v202, v202
	v_rcp_f32_e32 v203, v203
	v_rcp_f32_e32 v205, v168
	v_pk_mul_f32 v[150:151], v[150:151], v[202:203]
	v_pk_mul_f32 v[148:149], v[148:149], v[204:205]
	v_pk_mul_f32 v[150:151], v[146:147], v[150:151]
	v_pk_mul_f32 v[146:147], v[144:145], v[148:149]
	v_mov_b64_e32 v[148:149], s[10:11]
	v_mad_i64_i32 v[148:149], s[12:13], v192, s66, v[148:149]
	v_cvt_pk_bf16_f32 v144, v152, v153
	v_cvt_pk_bf16_f32 v145, v154, v155
	v_cvt_pk_bf16_f32 v146, v146, v147
	v_cvt_pk_bf16_f32 v147, v150, v151
	v_lshl_add_u64 v[148:149], v[174:175], 1, v[148:149]
	global_store_dwordx4 v[148:149], v[144:147], off nt
.LBB0_930:
	s_andn2_saveexec_b64 s[4:5], s[4:5]
	s_cbranch_execz .LBB0_932
	v_or_b32_e32 v202, 16, v202
	v_lshl_add_u64 v[152:153], s[24:25], 0, v[202:203]
	global_store_dwordx4 v[152:153], v[148:151], off nt
	s_nop 1
	v_lshl_add_u64 v[148:149], s[38:39], 0, v[202:203]
	global_store_dwordx4 v[148:149], v[144:147], off nt
.LBB0_932:
	s_or_b64 exec, exec, s[4:5]
	s_nop 0
	v_fmamk_f32 v144, v217, 0x3a000000, v215
	v_rsq_f32_e32 v148, v144
	v_add_u32_e32 v168, -14, v184
	v_lshl_add_u64 v[146:147], s[62:63], 0, v[168:169]
	v_mad_u64_u32 v[144:145], s[12:13], v146, s30, 0
	v_pk_mul_f32 v[142:143], v[142:143], v[148:149] op_sel_hi:[1,0]
	v_pk_mul_f32 v[140:141], v[140:141], v[148:149] op_sel_hi:[1,0]
	ds_bpermute_b32 v192, v179, v142
	ds_bpermute_b32 v203, v179, v143
	ds_bpermute_b32 v156, v179, v140
	ds_bpermute_b32 v158, v179, v141
	ds_bpermute_b32 v159, v177, v142
	ds_bpermute_b32 v202, v177, v143
	ds_bpermute_b32 v149, v177, v140
	ds_bpermute_b32 v157, v177, v141
	s_waitcnt lgkmcnt(7)
	v_cndmask_b32_e64 v154, v223, v192, s[0:1]
	s_waitcnt lgkmcnt(6)
	v_cndmask_b32_e64 v155, v225, v203, s[0:1]
	s_waitcnt lgkmcnt(5)
	v_cndmask_b32_e64 v150, v219, v156, s[0:1]
	s_waitcnt lgkmcnt(4)
	v_cndmask_b32_e64 v151, v221, v158, s[0:1]
	s_waitcnt lgkmcnt(3)
	v_cndmask_b32_e32 v152, v222, v159, vcc
	s_waitcnt lgkmcnt(2)
	v_cndmask_b32_e32 v153, v224, v202, vcc
	v_pk_fma_f32 v[154:155], v[74:75], v[154:155], v[78:79]
	v_mad_i32_i24 v145, v147, s30, v145
	s_waitcnt lgkmcnt(1)
	v_cndmask_b32_e32 v146, v218, v149, vcc
	s_waitcnt lgkmcnt(0)
; __device__ __forceinline__ unsigned cvt_pk_bf16(float lo, float hi) { unsigned r; asm volatile("v_cvt_pk_bf16_f32 %0, %1, %2" : "=v"(r) : "v"(lo), "v"(hi)); return r; }
;     __device__ __forceinline__ void operator()(EPI_ARGS) const {
;     ...
;             for (int m = 0; m < 4; ++m) {
;                 const int row = ROW_OF(ai, m);
;                 const float rs = __builtin_amdgcn_rsqf(rsv[ai][m] * (1.0f / D) + EPS);
;                 f32x4 o[2];
; #pragma unroll
;                 for (int n = 0; n < 2; ++n) {
;                     const f32x4 gv = acc[ai][0][m][n] * rs, vv = acc[ai][1][m][n] * rs;
;                     f32x4 r1, r2;
; #pragma unroll
;                     for (int j = 0; j < 4; ++j) { r1[j] = __shfl(gv[j], src1); r2[j] = __shfl(gv[j], src2); }
;                     f32x4 p1, p2;
; #pragma unroll
;                     for (int j = 0; j < 4; ++j) { p1[j] = fr >= 1 ? r1[j] : q1[n][j]; p2[j] = fr >= 2 ? r2[j] : q2[n][j]; }
;                     q1[n] = r1; q2[n] = r2;
;                     const f32x4 cv = bb[n] + w0[n] * p2 + w1[n] * p1 + w2[n] * gv;
;                     o[n] = gelu4(cv) * vv;
;                     if (m == 0 && fr < 2) { const size_t so = ((size_t)blk * 2 + fr) * FF + f0 + 4 * n; *(f32x4*)(headg + so) = gv; *(f32x4*)(headv + so) = vv; }
;                     if (m == 3 && fr >= 14) { const size_t so = ((size_t)blk * 2 + (fr - 14)) * FF + f0 + 4 * n; *(f32x4*)(tailg + so) = gv; }
;                 }
;                 if (!(m == 0 && fr < 2)) {
;                     u32x4 w; w.x = cvt_pk_bf16(o[0][0], o[0][1]); w.y = cvt_pk_bf16(o[0][2], o[0][3]); w.z = cvt_pk_bf16(o[1][0], o[1][1]); w.w = cvt_pk_bf16(o[1][2], o[1][3]);
;                     *(u32x4*)(act + (size_t)row * FF + f0) = w;
	v_cndmask_b32_e32 v147, v220, v157, vcc
	v_pk_fma_f32 v[150:151], v[72:73], v[150:151], v[76:77]
	v_pk_fma_f32 v[152:153], v[66:67], v[152:153], v[154:155]
	v_pk_fma_f32 v[146:147], v[64:65], v[146:147], v[150:151]
	v_pk_fma_f32 v[142:143], v[70:71], v[142:143], v[152:153]
	v_pk_fma_f32 v[140:141], v[68:69], v[140:141], v[146:147]
	v_pk_mul_f32 v[146:147], v[142:143], v[142:143]
	v_pk_mul_f32 v[150:151], v[140:141], v[140:141]
	v_fmamk_f32 v146, v146, 0xbdd2d3e8, v216
	v_mul_f32_e32 v146, v142, v146
	v_fmamk_f32 v150, v150, 0xbdd2d3e8, v216
	v_fmamk_f32 v151, v151, 0xbdd2d3e8, v216
	v_exp_f32_e32 v152, v146
	v_fmamk_f32 v146, v147, 0xbdd2d3e8, v216
	v_mul_f32_e32 v150, v140, v150
	v_mul_f32_e32 v151, v141, v151
	v_mul_f32_e32 v146, v143, v146
	v_exp_f32_e32 v150, v150
	v_exp_f32_e32 v151, v151
	v_exp_f32_e32 v153, v146
	v_pk_mul_f32 v[138:139], v[138:139], v[148:149] op_sel_hi:[1,0]
	v_add_f32_e32 v146, 1.0, v150
	v_add_f32_e32 v147, 1.0, v151
	v_add_f32_e32 v150, 1.0, v152
	v_add_f32_e32 v151, 1.0, v153
	v_pk_mul_f32 v[136:137], v[136:137], v[148:149] op_sel_hi:[1,0]
	ds_bpermute_b32 v205, v179, v138
	ds_bpermute_b32 v218, v179, v139
	v_rcp_f32_e32 v150, v150
	v_rcp_f32_e32 v151, v151
	ds_bpermute_b32 v153, v179, v136
	ds_bpermute_b32 v155, v179, v137
	ds_bpermute_b32 v204, v177, v138
	ds_bpermute_b32 v217, v177, v139
	v_rcp_f32_e32 v146, v146
	v_rcp_f32_e32 v147, v147
	ds_bpermute_b32 v152, v177, v136
	ds_bpermute_b32 v154, v177, v137
	v_pk_mul_f32 v[134:135], v[134:135], v[148:149] op_sel_hi:[1,0]
	v_pk_mul_f32 v[142:143], v[142:143], v[150:151]
	s_waitcnt lgkmcnt(7)
	v_cndmask_b32_e64 v150, v200, v205, s[0:1]
	s_waitcnt lgkmcnt(6)
	v_cndmask_b32_e64 v151, v201, v218, s[0:1]
	v_pk_mul_f32 v[132:133], v[132:133], v[148:149] op_sel_hi:[1,0]
	v_pk_mul_f32 v[140:141], v[140:141], v[146:147]
	v_pk_mul_f32 v[134:135], v[134:135], v[142:143]
	s_waitcnt lgkmcnt(5)
	v_cndmask_b32_e64 v142, v198, v153, s[0:1]
	s_waitcnt lgkmcnt(4)
	v_cndmask_b32_e64 v143, v199, v155, s[0:1]
	s_waitcnt lgkmcnt(3)
	v_cndmask_b32_e32 v146, v196, v204, vcc
	s_waitcnt lgkmcnt(2)
	v_cndmask_b32_e32 v147, v197, v217, vcc
	v_pk_fma_f32 v[150:151], v[94:95], v[150:151], v[98:99]
	v_pk_mul_f32 v[132:133], v[132:133], v[140:141]
	s_waitcnt lgkmcnt(1)
	v_cndmask_b32_e32 v140, v194, v152, vcc
	s_waitcnt lgkmcnt(0)
	v_cndmask_b32_e32 v141, v195, v154, vcc
	v_pk_fma_f32 v[142:143], v[92:93], v[142:143], v[96:97]
	v_pk_fma_f32 v[146:147], v[86:87], v[146:147], v[150:151]
	v_pk_fma_f32 v[140:141], v[84:85], v[140:141], v[142:143]
	v_pk_fma_f32 v[138:139], v[90:91], v[138:139], v[146:147]
	v_pk_fma_f32 v[136:137], v[88:89], v[136:137], v[140:141]
	v_pk_mul_f32 v[140:141], v[138:139], v[138:139]
	v_pk_mul_f32 v[142:143], v[136:137], v[136:137]
	v_fmamk_f32 v140, v140, 0xbdd2d3e8, v216
	v_fmamk_f32 v142, v142, 0xbdd2d3e8, v216
	v_fmamk_f32 v143, v143, 0xbdd2d3e8, v216
	v_mul_f32_e32 v140, v138, v140
	v_mul_f32_e32 v142, v136, v142
	v_mul_f32_e32 v143, v137, v143
	v_exp_f32_e32 v146, v140
	v_fmamk_f32 v140, v141, 0xbdd2d3e8, v216
	v_exp_f32_e32 v142, v142
	v_exp_f32_e32 v143, v143
	v_mul_f32_e32 v140, v139, v140
	v_exp_f32_e32 v147, v140
	v_add_f32_e32 v140, 1.0, v142
	v_add_f32_e32 v141, 1.0, v143
	v_rcp_f32_e32 v140, v140
	v_rcp_f32_e32 v141, v141
	v_add_f32_e32 v142, 1.0, v146
	v_add_f32_e32 v143, 1.0, v147
	v_rcp_f32_e32 v142, v142
	v_rcp_f32_e32 v143, v143
	v_pk_mul_f32 v[128:129], v[128:129], v[148:149] op_sel_hi:[1,0]
	v_pk_mul_f32 v[136:137], v[136:137], v[140:141]
	v_pk_mul_f32 v[130:131], v[130:131], v[148:149] op_sel_hi:[1,0]
	v_pk_mul_f32 v[138:139], v[138:139], v[142:143]
	v_pk_mul_f32 v[128:129], v[128:129], v[136:137]
	v_pk_mul_f32 v[138:139], v[130:131], v[138:139]
	v_cvt_pk_bf16_f32 v130, v132, v133
	v_cvt_pk_bf16_f32 v131, v134, v135
	v_cvt_pk_bf16_f32 v132, v128, v129
	v_fmamk_f32 v128, v193, 0x3a000000, v215
	v_cvt_pk_bf16_f32 v133, v138, v139
	v_rsq_f32_e32 v138, v128
	v_mov_b64_e32 v[136:137], s[10:11]
	v_mad_i64_i32 v[134:135], s[12:13], v190, s66, v[136:137]
	v_lshlrev_b64 v[128:129], 1, v[174:175]
	v_lshl_add_u64 v[134:135], v[134:135], 0, v[128:129]
	v_pk_mul_f32 v[140:141], v[124:125], v[138:139] op_sel_hi:[1,0]
	global_store_dwordx4 v[134:135], v[130:133], off nt
	v_pk_mul_f32 v[134:135], v[126:127], v[138:139] op_sel_hi:[1,0]
	ds_bpermute_b32 v125, v179, v140
	ds_bpermute_b32 v127, v179, v141
	ds_bpermute_b32 v124, v177, v140
	ds_bpermute_b32 v126, v177, v141
	ds_bpermute_b32 v131, v179, v134
	ds_bpermute_b32 v133, v179, v135
	ds_bpermute_b32 v130, v177, v134
	ds_bpermute_b32 v132, v177, v135
	s_waitcnt lgkmcnt(7)
	v_cndmask_b32_e64 v146, v156, v125, s[0:1]
	s_waitcnt lgkmcnt(6)
	v_cndmask_b32_e64 v147, v158, v127, s[0:1]
	s_waitcnt lgkmcnt(5)
	v_cndmask_b32_e32 v142, v149, v124, vcc
	s_waitcnt lgkmcnt(4)
	v_cndmask_b32_e32 v143, v157, v126, vcc
	s_waitcnt lgkmcnt(3)
	v_cndmask_b32_e64 v150, v192, v131, s[0:1]
	s_waitcnt lgkmcnt(2)
	v_cndmask_b32_e64 v151, v203, v133, s[0:1]
	v_pk_fma_f32 v[146:147], v[72:73], v[146:147], v[76:77]
	s_waitcnt lgkmcnt(1)
	v_cndmask_b32_e32 v148, v159, v130, vcc
	s_waitcnt lgkmcnt(0)
; __device__ __forceinline__ unsigned cvt_pk_bf16(float lo, float hi) { unsigned r; asm volatile("v_cvt_pk_bf16_f32 %0, %1, %2" : "=v"(r) : "v"(lo), "v"(hi)); return r; }
;     __device__ __forceinline__ void operator()(EPI_ARGS) const {
;     ...
;             for (int m = 0; m < 4; ++m) {
;                 const int row = ROW_OF(ai, m);
;                 const float rs = __builtin_amdgcn_rsqf(rsv[ai][m] * (1.0f / D) + EPS);
;                 f32x4 o[2];
; #pragma unroll
;                 for (int n = 0; n < 2; ++n) {
;                     const f32x4 gv = acc[ai][0][m][n] * rs, vv = acc[ai][1][m][n] * rs;
;                     f32x4 r1, r2;
; #pragma unroll
;                     for (int j = 0; j < 4; ++j) { r1[j] = __shfl(gv[j], src1); r2[j] = __shfl(gv[j], src2); }
;                     f32x4 p1, p2;
; #pragma unroll
;                     for (int j = 0; j < 4; ++j) { p1[j] = fr >= 1 ? r1[j] : q1[n][j]; p2[j] = fr >= 2 ? r2[j] : q2[n][j]; }
;                     q1[n] = r1; q2[n] = r2;
;                     const f32x4 cv = bb[n] + w0[n] * p2 + w1[n] * p1 + w2[n] * gv;
;                     o[n] = gelu4(cv) * vv;
;                     if (m == 0 && fr < 2) { const size_t so = ((size_t)blk * 2 + fr) * FF + f0 + 4 * n; *(f32x4*)(headg + so) = gv; *(f32x4*)(headv + so) = vv; }
;                     if (m == 3 && fr >= 14) { const size_t so = ((size_t)blk * 2 + (fr - 14)) * FF + f0 + 4 * n; *(f32x4*)(tailg + so) = gv; }
;                 }
;                 if (!(m == 0 && fr < 2)) {
;                     u32x4 w; w.x = cvt_pk_bf16(o[0][0], o[0][1]); w.y = cvt_pk_bf16(o[0][2], o[0][3]); w.z = cvt_pk_bf16(o[1][0], o[1][1]); w.w = cvt_pk_bf16(o[1][2], o[1][3]);
;                     *(u32x4*)(act + (size_t)row * FF + f0) = w;
	v_cndmask_b32_e32 v149, v202, v132, vcc
	v_pk_fma_f32 v[150:151], v[74:75], v[150:151], v[78:79]
	v_pk_fma_f32 v[142:143], v[64:65], v[142:143], v[146:147]
	v_pk_fma_f32 v[148:149], v[66:67], v[148:149], v[150:151]
	v_pk_fma_f32 v[140:141], v[68:69], v[140:141], v[142:143]
	v_pk_fma_f32 v[134:135], v[70:71], v[134:135], v[148:149]
	v_pk_mul_f32 v[146:147], v[140:141], v[140:141]
	v_pk_mul_f32 v[142:143], v[134:135], v[134:135]
	v_fmamk_f32 v139, v146, 0xbdd2d3e8, v216
	v_mul_f32_e32 v139, v140, v139
	v_fmamk_f32 v146, v147, 0xbdd2d3e8, v216
	v_fmamk_f32 v142, v142, 0xbdd2d3e8, v216
	v_exp_f32_e32 v139, v139
	v_mul_f32_e32 v146, v141, v146
	v_mul_f32_e32 v142, v134, v142
	v_exp_f32_e32 v146, v146
	v_exp_f32_e32 v147, v142
	v_fmamk_f32 v142, v143, 0xbdd2d3e8, v216
	v_mul_f32_e32 v142, v135, v142
	v_exp_f32_e32 v148, v142
	v_add_f32_e32 v139, 1.0, v139
	v_rcp_f32_e32 v142, v139
	v_add_f32_e32 v139, 1.0, v146
	v_rcp_f32_e32 v143, v139
	v_add_f32_e32 v139, 1.0, v147
	v_rcp_f32_e32 v146, v139
	v_add_f32_e32 v139, 1.0, v148
	v_rcp_f32_e32 v147, v139
	v_pk_mul_f32 v[116:117], v[116:117], v[138:139] op_sel_hi:[1,0]
	v_pk_mul_f32 v[118:119], v[118:119], v[138:139] op_sel_hi:[1,0]
	v_pk_mul_f32 v[140:141], v[140:141], v[142:143]
	v_pk_mul_f32 v[134:135], v[134:135], v[146:147]
	v_pk_mul_f32 v[146:147], v[120:121], v[138:139] op_sel_hi:[1,0]
	v_pk_mul_f32 v[142:143], v[118:119], v[134:135]
	v_pk_mul_f32 v[116:117], v[116:117], v[140:141]
	v_pk_mul_f32 v[140:141], v[122:123], v[138:139] op_sel_hi:[1,0]
	ds_bpermute_b32 v119, v179, v146
	ds_bpermute_b32 v121, v179, v147
	ds_bpermute_b32 v118, v177, v146
	ds_bpermute_b32 v120, v177, v147
	ds_bpermute_b32 v123, v179, v140
	ds_bpermute_b32 v135, v179, v141
	ds_bpermute_b32 v122, v177, v140
	ds_bpermute_b32 v134, v177, v141
	s_waitcnt lgkmcnt(7)
	v_cndmask_b32_e64 v150, v153, v119, s[0:1]
	s_waitcnt lgkmcnt(6)
	v_cndmask_b32_e64 v151, v155, v121, s[0:1]
	s_waitcnt lgkmcnt(5)
	v_cndmask_b32_e32 v148, v152, v118, vcc
	s_waitcnt lgkmcnt(4)
	v_cndmask_b32_e32 v149, v154, v120, vcc
	s_waitcnt lgkmcnt(3)
	v_cndmask_b32_e64 v154, v205, v123, s[0:1]
	s_waitcnt lgkmcnt(2)
	v_cndmask_b32_e64 v155, v218, v135, s[0:1]
	v_pk_fma_f32 v[150:151], v[92:93], v[150:151], v[96:97]
	s_waitcnt lgkmcnt(1)
	v_cndmask_b32_e32 v152, v204, v122, vcc
	s_waitcnt lgkmcnt(0)
	v_cndmask_b32_e32 v153, v217, v134, vcc
	v_pk_fma_f32 v[154:155], v[94:95], v[154:155], v[98:99]
	v_pk_fma_f32 v[148:149], v[84:85], v[148:149], v[150:151]
	v_pk_fma_f32 v[152:153], v[86:87], v[152:153], v[154:155]
	v_pk_fma_f32 v[146:147], v[88:89], v[146:147], v[148:149]
	v_pk_fma_f32 v[140:141], v[90:91], v[140:141], v[152:153]
	v_pk_mul_f32 v[150:151], v[146:147], v[146:147]
	v_pk_mul_f32 v[148:149], v[140:141], v[140:141]
	v_fmamk_f32 v139, v150, 0xbdd2d3e8, v216
	v_mul_f32_e32 v139, v146, v139
	v_fmamk_f32 v150, v151, 0xbdd2d3e8, v216
	v_fmamk_f32 v148, v148, 0xbdd2d3e8, v216
	v_exp_f32_e32 v139, v139
	v_mul_f32_e32 v150, v147, v150
	v_mul_f32_e32 v148, v140, v148
	v_exp_f32_e32 v150, v150
	v_exp_f32_e32 v151, v148
	v_fmamk_f32 v148, v149, 0xbdd2d3e8, v216
	v_mul_f32_e32 v148, v141, v148
	v_exp_f32_e32 v152, v148
	v_add_f32_e32 v139, 1.0, v139
	v_rcp_f32_e32 v148, v139
	v_add_f32_e32 v139, 1.0, v150
	v_rcp_f32_e32 v149, v139
	v_add_f32_e32 v139, 1.0, v151
	v_rcp_f32_e32 v150, v139
	v_add_f32_e32 v139, 1.0, v152
	v_rcp_f32_e32 v151, v139
	v_pk_mul_f32 v[112:113], v[112:113], v[138:139] op_sel_hi:[1,0]
	v_pk_mul_f32 v[114:115], v[114:115], v[138:139] op_sel_hi:[1,0]
	v_pk_mul_f32 v[138:139], v[146:147], v[148:149]
	v_pk_mul_f32 v[140:141], v[140:141], v[150:151]
	v_pk_mul_f32 v[112:113], v[112:113], v[138:139]
	v_pk_mul_f32 v[140:141], v[114:115], v[140:141]
	v_cvt_pk_bf16_f32 v114, v116, v117
	v_cvt_pk_bf16_f32 v115, v142, v143
	v_cvt_pk_bf16_f32 v116, v112, v113
	v_fmamk_f32 v112, v191, 0x3a000000, v215
	v_rsq_f32_e32 v112, v112
	v_cvt_pk_bf16_f32 v117, v140, v141
	v_mad_i64_i32 v[146:147], s[12:13], v188, s66, v[136:137]
	v_pk_mul_f32 v[110:111], v[110:111], v[112:113] op_sel_hi:[1,0]
	v_pk_mul_f32 v[108:109], v[108:109], v[112:113] op_sel_hi:[1,0]
	ds_bpermute_b32 v136, v177, v108
	ds_bpermute_b32 v137, v179, v108
	ds_bpermute_b32 v138, v177, v109
	ds_bpermute_b32 v139, v179, v109
	ds_bpermute_b32 v140, v177, v110
	ds_bpermute_b32 v141, v179, v110
	ds_bpermute_b32 v142, v177, v111
	ds_bpermute_b32 v143, v179, v111
	v_lshl_add_u64 v[146:147], v[146:147], 0, v[128:129]
	global_store_dwordx4 v[146:147], v[114:117], off nt
	v_cmp_lt_i32_e64 s[4:5], 13, v184
	s_nop 0
	v_lshl_add_u64 v[114:115], s[40:41], 0, v[144:145]
	v_lshl_add_u64 v[116:117], v[174:175], 2, v[114:115]
	s_and_saveexec_b64 s[12:13], s[4:5]
	s_cbranch_execz .LBB0_934
	global_store_dwordx4 v[116:117], v[108:111], off nt
.LBB0_934:
	s_or_b64 exec, exec, s[12:13]
	v_mov_b32_e32 v113, v112
	v_mov_b32_e32 v114, v112
	v_mov_b32_e32 v115, v112
	v_pk_mul_f32 v[106:107], v[106:107], v[114:115]
	v_pk_mul_f32 v[104:105], v[104:105], v[112:113]
	ds_bpermute_b32 v144, v177, v104
	ds_bpermute_b32 v145, v179, v104
	ds_bpermute_b32 v146, v177, v105
	ds_bpermute_b32 v147, v179, v105
	ds_bpermute_b32 v148, v177, v106
	ds_bpermute_b32 v149, v179, v106
	ds_bpermute_b32 v150, v177, v107
	ds_bpermute_b32 v151, v179, v107
	s_and_saveexec_b64 s[12:13], s[4:5]
	s_cbranch_execz .LBB0_936
	global_store_dwordx4 v[116:117], v[104:107], off offset:16 nt
; __device__ __forceinline__ unsigned cvt_pk_bf16(float lo, float hi) { unsigned r; asm volatile("v_cvt_pk_bf16_f32 %0, %1, %2" : "=v"(r) : "v"(lo), "v"(hi)); return r; }
;     __device__ __forceinline__ void operator()(EPI_ARGS) const {
;     ...
;             for (int m = 0; m < 4; ++m) {
;                 const int row = ROW_OF(ai, m);
;                 const float rs = __builtin_amdgcn_rsqf(rsv[ai][m] * (1.0f / D) + EPS);
;                 f32x4 o[2];
; #pragma unroll
;                 for (int n = 0; n < 2; ++n) {
;                     const f32x4 gv = acc[ai][0][m][n] * rs, vv = acc[ai][1][m][n] * rs;
;                     f32x4 r1, r2;
; #pragma unroll
;                     for (int j = 0; j < 4; ++j) { r1[j] = __shfl(gv[j], src1); r2[j] = __shfl(gv[j], src2); }
;                     f32x4 p1, p2;
; #pragma unroll
;                     for (int j = 0; j < 4; ++j) { p1[j] = fr >= 1 ? r1[j] : q1[n][j]; p2[j] = fr >= 2 ? r2[j] : q2[n][j]; }
;                     q1[n] = r1; q2[n] = r2;
;                     const f32x4 cv = bb[n] + w0[n] * p2 + w1[n] * p1 + w2[n] * gv;
;                     o[n] = gelu4(cv) * vv;
;                     if (m == 0 && fr < 2) { const size_t so = ((size_t)blk * 2 + fr) * FF + f0 + 4 * n; *(f32x4*)(headg + so) = gv; *(f32x4*)(headv + so) = vv; }
;                     if (m == 3 && fr >= 14) { const size_t so = ((size_t)blk * 2 + (fr - 14)) * FF + f0 + 4 * n; *(f32x4*)(tailg + so) = gv; }
;                 }
;                 if (!(m == 0 && fr < 2)) {
;                     u32x4 w; w.x = cvt_pk_bf16(o[0][0], o[0][1]); w.y = cvt_pk_bf16(o[0][2], o[0][3]); w.z = cvt_pk_bf16(o[1][0], o[1][1]); w.w = cvt_pk_bf16(o[1][2], o[1][3]);
;                     *(u32x4*)(act + (size_t)row * FF + f0) = w;
.LBB0_936:
	s_or_b64 exec, exec, s[12:13]
	s_waitcnt lgkmcnt(5)
	v_cndmask_b32_e32 v117, v120, v146, vcc
	s_waitcnt lgkmcnt(3)
	v_cndmask_b32_e32 v120, v122, v148, vcc
	s_waitcnt lgkmcnt(2)
	v_cndmask_b32_e64 v122, v123, v149, s[0:1]
	s_waitcnt lgkmcnt(0)
	v_cndmask_b32_e64 v123, v135, v151, s[0:1]
	v_cndmask_b32_e32 v116, v118, v144, vcc
	v_cndmask_b32_e64 v118, v119, v145, s[0:1]
	v_cndmask_b32_e64 v119, v121, v147, s[0:1]
	v_cndmask_b32_e32 v121, v134, v150, vcc
	v_pk_fma_f32 v[122:123], v[94:95], v[122:123], v[98:99]
	v_pk_fma_f32 v[118:119], v[92:93], v[118:119], v[96:97]
	v_pk_fma_f32 v[120:121], v[86:87], v[120:121], v[122:123]
	v_pk_fma_f32 v[116:117], v[84:85], v[116:117], v[118:119]
	v_pk_fma_f32 v[106:107], v[90:91], v[106:107], v[120:121]
	v_pk_fma_f32 v[104:105], v[88:89], v[104:105], v[116:117]
	v_pk_mul_f32 v[116:117], v[106:107], v[106:107]
	v_pk_mul_f32 v[118:119], v[104:105], v[104:105]
	v_fmamk_f32 v116, v116, 0xbdd2d3e8, v216
	v_mul_f32_e32 v116, v106, v116
	v_fmamk_f32 v118, v118, 0xbdd2d3e8, v216
	v_fmamk_f32 v119, v119, 0xbdd2d3e8, v216
	v_exp_f32_e32 v120, v116
	v_fmamk_f32 v116, v117, 0xbdd2d3e8, v216
	v_mul_f32_e32 v118, v104, v118
	v_mul_f32_e32 v119, v105, v119
	v_mul_f32_e32 v116, v107, v116
	v_exp_f32_e32 v118, v118
	v_exp_f32_e32 v119, v119
	v_exp_f32_e32 v121, v116
	v_pk_mul_f32 v[102:103], v[102:103], v[114:115]
	v_add_f32_e32 v116, 1.0, v118
	v_add_f32_e32 v117, 1.0, v119
	v_add_f32_e32 v118, 1.0, v120
	v_add_f32_e32 v119, 1.0, v121
	v_rcp_f32_e32 v118, v118
	v_rcp_f32_e32 v119, v119
	v_rcp_f32_e32 v116, v116
	v_rcp_f32_e32 v117, v117
	v_pk_mul_f32 v[100:101], v[100:101], v[112:113]
	v_pk_mul_f32 v[106:107], v[106:107], v[118:119]
	v_cndmask_b32_e64 v118, v131, v141, s[0:1]
	v_cndmask_b32_e64 v119, v133, v143, s[0:1]
	v_pk_mul_f32 v[104:105], v[104:105], v[116:117]
	v_pk_mul_f32 v[102:103], v[102:103], v[106:107]
	v_cndmask_b32_e64 v106, v125, v137, s[0:1]
	v_cndmask_b32_e64 v107, v127, v139, s[0:1]
	v_cndmask_b32_e32 v116, v130, v140, vcc
	v_cndmask_b32_e32 v117, v132, v142, vcc
	v_pk_fma_f32 v[118:119], v[74:75], v[118:119], v[78:79]
	v_pk_mul_f32 v[100:101], v[100:101], v[104:105]
	v_cndmask_b32_e32 v104, v124, v136, vcc
	v_cndmask_b32_e32 v105, v126, v138, vcc
	v_pk_fma_f32 v[106:107], v[72:73], v[106:107], v[76:77]
	v_pk_fma_f32 v[116:117], v[66:67], v[116:117], v[118:119]
	v_pk_fma_f32 v[104:105], v[64:65], v[104:105], v[106:107]
	v_pk_fma_f32 v[106:107], v[70:71], v[110:111], v[116:117]
	v_pk_fma_f32 v[104:105], v[68:69], v[108:109], v[104:105]
	v_pk_mul_f32 v[108:109], v[106:107], v[106:107]
	v_pk_mul_f32 v[110:111], v[104:105], v[104:105]
	v_fmamk_f32 v108, v108, 0xbdd2d3e8, v216
	v_mul_f32_e32 v108, v106, v108
	v_fmamk_f32 v110, v110, 0xbdd2d3e8, v216
	v_fmamk_f32 v111, v111, 0xbdd2d3e8, v216
	v_exp_f32_e32 v116, v108
	v_fmamk_f32 v108, v109, 0xbdd2d3e8, v216
	v_mul_f32_e32 v110, v104, v110
	v_mul_f32_e32 v111, v105, v111
	v_mul_f32_e32 v108, v107, v108
	v_exp_f32_e32 v110, v110
	v_exp_f32_e32 v111, v111
	v_exp_f32_e32 v117, v108
	v_pk_mul_f32 v[82:83], v[82:83], v[114:115]
	v_add_f32_e32 v108, 1.0, v110
	v_add_f32_e32 v109, 1.0, v111
	v_add_f32_e32 v110, 1.0, v116
	v_add_f32_e32 v111, 1.0, v117
	v_rcp_f32_e32 v108, v108
	v_rcp_f32_e32 v109, v109
	v_rcp_f32_e32 v110, v110
	v_rcp_f32_e32 v111, v111
	v_pk_mul_f32 v[80:81], v[80:81], v[112:113]
	v_pk_mul_f32 v[104:105], v[104:105], v[108:109]
	v_pk_mul_f32 v[106:107], v[106:107], v[110:111]
	s_nop 0
	v_pk_mul_f32 v[82:83], v[82:83], v[106:107]
	v_pk_mul_f32 v[80:81], v[80:81], v[104:105]
	s_nop 0
	v_cvt_pk_bf16_f32 v80, v80, v81
	v_cvt_pk_bf16_f32 v81, v82, v83
	v_cvt_pk_bf16_f32 v82, v100, v101
	v_mov_b64_e32 v[100:101], s[10:11]
	v_mad_i64_i32 v[100:101], s[12:13], v186, s66, v[100:101]
	v_lshl_add_u64 v[100:101], v[174:175], 1, v[100:101]
	v_cvt_pk_bf16_f32 v83, v102, v103
	global_store_dwordx4 v[100:101], v[80:83], off nt
	s_add_i32 s12, s60, 2
	s_ashr_i32 s13, s12, 31
	v_fmamk_f32 v80, v189, 0x3a000000, v215
	v_rsq_f32_e32 v106, v80
	s_lshl_b64 s[60:61], s[12:13], 1
	v_lshl_add_u64 v[80:81], s[60:61], 0, v[184:185]
	v_mad_u64_u32 v[82:83], s[12:13], v80, s65, v[174:175]
	v_pk_mul_f32 v[62:63], v[62:63], v[106:107] op_sel_hi:[1,0]
	v_pk_mul_f32 v[60:61], v[60:61], v[106:107] op_sel_hi:[1,0]
	ds_bpermute_b32 v108, v177, v60
	ds_bpermute_b32 v109, v179, v60
	ds_bpermute_b32 v110, v177, v61
	ds_bpermute_b32 v111, v179, v61
	ds_bpermute_b32 v112, v177, v62
	ds_bpermute_b32 v113, v179, v62
	ds_bpermute_b32 v114, v177, v63
	ds_bpermute_b32 v115, v179, v63
	v_mad_i32_i24 v83, v81, s65, v83
	v_pk_mul_f32 v[54:55], v[54:55], v[106:107] op_sel_hi:[1,0]
	v_pk_mul_f32 v[52:53], v[52:53], v[106:107] op_sel_hi:[1,0]
	v_lshlrev_b64 v[104:105], 2, v[82:83]
	s_and_saveexec_b64 s[12:13], s[8:9]
	s_cbranch_execz .LBB0_938
	v_lshl_add_u64 v[82:83], s[24:25], 0, v[104:105]
	v_lshl_add_u64 v[80:81], s[38:39], 0, v[104:105]
	global_store_dwordx4 v[82:83], v[60:63], off nt
	global_store_dwordx4 v[80:81], v[52:55], off nt
; __device__ __forceinline__ unsigned cvt_pk_bf16(float lo, float hi) { unsigned r; asm volatile("v_cvt_pk_bf16_f32 %0, %1, %2" : "=v"(r) : "v"(lo), "v"(hi)); return r; }
;     __device__ __forceinline__ void operator()(EPI_ARGS) const {
;     ...
;             for (int m = 0; m < 4; ++m) {
;                 const int row = ROW_OF(ai, m);
;                 const float rs = __builtin_amdgcn_rsqf(rsv[ai][m] * (1.0f / D) + EPS);
;                 f32x4 o[2];
; #pragma unroll
;                 for (int n = 0; n < 2; ++n) {
;                     const f32x4 gv = acc[ai][0][m][n] * rs, vv = acc[ai][1][m][n] * rs;
;                     f32x4 r1, r2;
; #pragma unroll
;                     for (int j = 0; j < 4; ++j) { r1[j] = __shfl(gv[j], src1); r2[j] = __shfl(gv[j], src2); }
;                     f32x4 p1, p2;
; #pragma unroll
;                     for (int j = 0; j < 4; ++j) { p1[j] = fr >= 1 ? r1[j] : q1[n][j]; p2[j] = fr >= 2 ? r2[j] : q2[n][j]; }
;                     q1[n] = r1; q2[n] = r2;
;                     const f32x4 cv = bb[n] + w0[n] * p2 + w1[n] * p1 + w2[n] * gv;
;                     o[n] = gelu4(cv) * vv;
;                     if (m == 0 && fr < 2) { const size_t so = ((size_t)blk * 2 + fr) * FF + f0 + 4 * n; *(f32x4*)(headg + so) = gv; *(f32x4*)(headv + so) = vv; }
;                     if (m == 3 && fr >= 14) { const size_t so = ((size_t)blk * 2 + (fr - 14)) * FF + f0 + 4 * n; *(f32x4*)(tailg + so) = gv; }
;                 }
;                 if (!(m == 0 && fr < 2)) {
;                     u32x4 w; w.x = cvt_pk_bf16(o[0][0], o[0][1]); w.y = cvt_pk_bf16(o[0][2], o[0][3]); w.z = cvt_pk_bf16(o[1][0], o[1][1]); w.w = cvt_pk_bf16(o[1][2], o[1][3]);
;                     *(u32x4*)(act + (size_t)row * FF + f0) = w;
.LBB0_938:
	s_or_b64 exec, exec, s[12:13]
	v_mov_b32_e32 v107, v106
	v_mov_b32_e32 v116, v106
	v_mov_b32_e32 v117, v106
	v_pk_mul_f32 v[58:59], v[58:59], v[116:117]
	v_pk_mul_f32 v[56:57], v[56:57], v[106:107]
	ds_bpermute_b32 v80, v177, v56
	ds_bpermute_b32 v100, v179, v56
	ds_bpermute_b32 v81, v177, v57
	ds_bpermute_b32 v101, v179, v57
	ds_bpermute_b32 v82, v177, v58
	ds_bpermute_b32 v102, v179, v58
	ds_bpermute_b32 v83, v177, v59
	ds_bpermute_b32 v103, v179, v59
	v_pk_mul_f32 v[50:51], v[50:51], v[116:117]
	v_pk_mul_f32 v[48:49], v[48:49], v[106:107]
	s_and_saveexec_b64 s[8:9], s[6:7]
	s_xor_b64 s[6:7], exec, s[8:9]
	s_cbranch_execz .LBB0_940
	s_waitcnt lgkmcnt(10)
	v_cndmask_b32_e64 v118, 0, v113, s[0:1]
	s_waitcnt lgkmcnt(8)
	v_cndmask_b32_e64 v119, 0, v115, s[0:1]
	v_cndmask_b32_e64 v106, 0, v109, s[0:1]
	v_cndmask_b32_e64 v107, 0, v111, s[0:1]
	v_cndmask_b32_e32 v116, 0, v112, vcc
	v_cndmask_b32_e32 v117, 0, v114, vcc
	v_pk_fma_f32 v[118:119], v[74:75], v[118:119], v[78:79]
	v_cndmask_b32_e32 v104, 0, v108, vcc
	v_cndmask_b32_e32 v105, 0, v110, vcc
	v_pk_fma_f32 v[106:107], v[72:73], v[106:107], v[76:77]
	v_pk_fma_f32 v[116:117], v[66:67], v[116:117], v[118:119]
	v_pk_fma_f32 v[104:105], v[64:65], v[104:105], v[106:107]
	v_pk_fma_f32 v[62:63], v[70:71], v[62:63], v[116:117]
	v_pk_fma_f32 v[60:61], v[68:69], v[60:61], v[104:105]
	v_pk_mul_f32 v[104:105], v[62:63], v[62:63]
	v_pk_mul_f32 v[106:107], v[60:61], v[60:61]
	v_fmamk_f32 v104, v104, 0xbdd2d3e8, v216
	v_mul_f32_e32 v104, v62, v104
	v_fmamk_f32 v106, v106, 0xbdd2d3e8, v216
	v_fmamk_f32 v107, v107, 0xbdd2d3e8, v216
	v_exp_f32_e32 v116, v104
	v_fmamk_f32 v104, v105, 0xbdd2d3e8, v216
	v_mul_f32_e32 v106, v60, v106
	v_mul_f32_e32 v107, v61, v107
	v_mul_f32_e32 v104, v63, v104
	v_exp_f32_e32 v106, v106
	v_exp_f32_e32 v107, v107
	v_exp_f32_e32 v117, v104
	v_add_f32_e32 v104, 1.0, v106
	v_add_f32_e32 v105, 1.0, v107
	v_add_f32_e32 v106, 1.0, v116
	v_add_f32_e32 v107, 1.0, v117
	v_rcp_f32_e32 v104, v104
	v_rcp_f32_e32 v105, v105
	v_rcp_f32_e32 v106, v106
	v_rcp_f32_e32 v107, v107
	v_pk_mul_f32 v[60:61], v[60:61], v[104:105]
	s_waitcnt lgkmcnt(0)
	v_pk_fma_f32 v[104:105], v[94:95], v[102:103], v[98:99]
	v_pk_mul_f32 v[62:63], v[62:63], v[106:107]
	v_pk_fma_f32 v[106:107], v[92:93], v[100:101], v[96:97]
	v_pk_fma_f32 v[104:105], v[86:87], v[82:83], v[104:105]
	v_pk_fma_f32 v[106:107], v[84:85], v[80:81], v[106:107]
	v_pk_fma_f32 v[58:59], v[90:91], v[58:59], v[104:105]
	v_pk_fma_f32 v[56:57], v[88:89], v[56:57], v[106:107]
	v_pk_mul_f32 v[104:105], v[58:59], v[58:59]
	v_pk_mul_f32 v[106:107], v[56:57], v[56:57]
	v_fmamk_f32 v104, v104, 0xbdd2d3e8, v216
	v_fmamk_f32 v106, v106, 0xbdd2d3e8, v216
	v_fmamk_f32 v107, v107, 0xbdd2d3e8, v216
	v_fmamk_f32 v105, v105, 0xbdd2d3e8, v216
	v_mul_f32_e32 v106, v56, v106
	v_mul_f32_e32 v107, v57, v107
	v_mul_f32_e32 v104, v58, v104
	v_mul_f32_e32 v105, v59, v105
	v_exp_f32_e32 v106, v106
	v_exp_f32_e32 v107, v107
	v_exp_f32_e32 v104, v104
	v_exp_f32_e32 v105, v105
	v_add_f32_e32 v106, 1.0, v106
	v_add_f32_e32 v107, 1.0, v107
	v_add_f32_e32 v104, 1.0, v104
	v_add_f32_e32 v105, 1.0, v105
	v_rcp_f32_e32 v106, v106
	v_rcp_f32_e32 v104, v104
	v_rcp_f32_e32 v105, v105
	v_rcp_f32_e32 v107, v107
	v_pk_mul_f32 v[52:53], v[52:53], v[60:61]
	v_pk_mul_f32 v[54:55], v[54:55], v[62:63]
	v_pk_mul_f32 v[58:59], v[58:59], v[104:105]
	v_pk_mul_f32 v[56:57], v[56:57], v[106:107]
	v_pk_mul_f32 v[58:59], v[50:51], v[58:59]
	v_pk_mul_f32 v[50:51], v[48:49], v[56:57]
	v_cvt_pk_bf16_f32 v48, v52, v53
	v_mov_b64_e32 v[52:53], s[10:11]
	v_mad_i64_i32 v[52:53], s[8:9], v182, s66, v[52:53]
	v_cvt_pk_bf16_f32 v49, v54, v55
	v_cvt_pk_bf16_f32 v50, v50, v51
	v_cvt_pk_bf16_f32 v51, v58, v59
	v_lshl_add_u64 v[52:53], v[174:175], 1, v[52:53]
	global_store_dwordx4 v[52:53], v[48:51], off nt
.LBB0_940:
	s_andn2_saveexec_b64 s[6:7], s[6:7]
	s_cbranch_execz .LBB0_942
	v_or_b32_e32 v104, 16, v104
	v_lshl_add_u64 v[52:53], s[24:25], 0, v[104:105]
	global_store_dwordx4 v[52:53], v[56:59], off nt
	v_lshl_add_u64 v[52:53], s[38:39], 0, v[104:105]
	global_store_dwordx4 v[52:53], v[48:51], off nt
.LBB0_942:
	s_or_b64 exec, exec, s[6:7]
	s_nop 0
	v_fmamk_f32 v48, v187, 0x3a000000, v215
	v_rsq_f32_e32 v52, v48
	v_lshl_add_u64 v[50:51], s[60:61], 0, v[168:169]
	v_mad_u64_u32 v[48:49], s[6:7], v50, s30, 0
	v_pk_mul_f32 v[46:47], v[46:47], v[52:53] op_sel_hi:[1,0]
	v_pk_mul_f32 v[44:45], v[44:45], v[52:53] op_sel_hi:[1,0]
	ds_bpermute_b32 v104, v179, v46
	ds_bpermute_b32 v106, v179, v47
	ds_bpermute_b32 v60, v179, v44
	ds_bpermute_b32 v62, v179, v45
	ds_bpermute_b32 v63, v177, v46
	ds_bpermute_b32 v105, v177, v47
	ds_bpermute_b32 v53, v177, v44
	ds_bpermute_b32 v61, v177, v45
	s_waitcnt lgkmcnt(7)
	v_cndmask_b32_e64 v58, v113, v104, s[0:1]
	s_waitcnt lgkmcnt(6)
	v_cndmask_b32_e64 v59, v115, v106, s[0:1]
	s_waitcnt lgkmcnt(5)
	v_cndmask_b32_e64 v54, v109, v60, s[0:1]
	s_waitcnt lgkmcnt(4)
	v_cndmask_b32_e64 v55, v111, v62, s[0:1]
	s_waitcnt lgkmcnt(3)
	v_cndmask_b32_e32 v56, v112, v63, vcc
	s_waitcnt lgkmcnt(2)
	v_cndmask_b32_e32 v57, v114, v105, vcc
	v_pk_fma_f32 v[58:59], v[74:75], v[58:59], v[78:79]
	v_mad_i32_i24 v49, v51, s30, v49
	s_waitcnt lgkmcnt(1)
	v_cndmask_b32_e32 v50, v108, v53, vcc
	s_waitcnt lgkmcnt(0)
; __device__ __forceinline__ unsigned cvt_pk_bf16(float lo, float hi) { unsigned r; asm volatile("v_cvt_pk_bf16_f32 %0, %1, %2" : "=v"(r) : "v"(lo), "v"(hi)); return r; }
;     __device__ __forceinline__ void operator()(EPI_ARGS) const {
;     ...
;             for (int m = 0; m < 4; ++m) {
;                 const int row = ROW_OF(ai, m);
;                 const float rs = __builtin_amdgcn_rsqf(rsv[ai][m] * (1.0f / D) + EPS);
;                 f32x4 o[2];
; #pragma unroll
;                 for (int n = 0; n < 2; ++n) {
;                     const f32x4 gv = acc[ai][0][m][n] * rs, vv = acc[ai][1][m][n] * rs;
;                     f32x4 r1, r2;
; #pragma unroll
;                     for (int j = 0; j < 4; ++j) { r1[j] = __shfl(gv[j], src1); r2[j] = __shfl(gv[j], src2); }
;                     f32x4 p1, p2;
; #pragma unroll
;                     for (int j = 0; j < 4; ++j) { p1[j] = fr >= 1 ? r1[j] : q1[n][j]; p2[j] = fr >= 2 ? r2[j] : q2[n][j]; }
;                     q1[n] = r1; q2[n] = r2;
;                     const f32x4 cv = bb[n] + w0[n] * p2 + w1[n] * p1 + w2[n] * gv;
;                     o[n] = gelu4(cv) * vv;
;                     if (m == 0 && fr < 2) { const size_t so = ((size_t)blk * 2 + fr) * FF + f0 + 4 * n; *(f32x4*)(headg + so) = gv; *(f32x4*)(headv + so) = vv; }
;                     if (m == 3 && fr >= 14) { const size_t so = ((size_t)blk * 2 + (fr - 14)) * FF + f0 + 4 * n; *(f32x4*)(tailg + so) = gv; }
;                 }
;                 if (!(m == 0 && fr < 2)) {
;                     u32x4 w; w.x = cvt_pk_bf16(o[0][0], o[0][1]); w.y = cvt_pk_bf16(o[0][2], o[0][3]); w.z = cvt_pk_bf16(o[1][0], o[1][1]); w.w = cvt_pk_bf16(o[1][2], o[1][3]);
;                     *(u32x4*)(act + (size_t)row * FF + f0) = w;
	v_cndmask_b32_e32 v51, v110, v61, vcc
	v_pk_fma_f32 v[54:55], v[72:73], v[54:55], v[76:77]
	v_pk_fma_f32 v[56:57], v[66:67], v[56:57], v[58:59]
	v_pk_fma_f32 v[50:51], v[64:65], v[50:51], v[54:55]
	v_pk_fma_f32 v[46:47], v[70:71], v[46:47], v[56:57]
	v_pk_fma_f32 v[44:45], v[68:69], v[44:45], v[50:51]
	v_pk_mul_f32 v[50:51], v[46:47], v[46:47]
	v_pk_mul_f32 v[54:55], v[44:45], v[44:45]
	v_fmamk_f32 v50, v50, 0xbdd2d3e8, v216
	v_mul_f32_e32 v50, v46, v50
	v_fmamk_f32 v54, v54, 0xbdd2d3e8, v216
	v_fmamk_f32 v55, v55, 0xbdd2d3e8, v216
	v_exp_f32_e32 v56, v50
	v_fmamk_f32 v50, v51, 0xbdd2d3e8, v216
	v_mul_f32_e32 v54, v44, v54
	v_mul_f32_e32 v55, v45, v55
	v_mul_f32_e32 v50, v47, v50
	v_exp_f32_e32 v54, v54
	v_exp_f32_e32 v55, v55
	v_exp_f32_e32 v57, v50
	v_pk_mul_f32 v[42:43], v[42:43], v[52:53] op_sel_hi:[1,0]
	v_add_f32_e32 v50, 1.0, v54
	v_add_f32_e32 v51, 1.0, v55
	v_add_f32_e32 v54, 1.0, v56
	v_add_f32_e32 v55, 1.0, v57
	v_pk_mul_f32 v[40:41], v[40:41], v[52:53] op_sel_hi:[1,0]
	ds_bpermute_b32 v108, v179, v42
	ds_bpermute_b32 v110, v179, v43
	v_rcp_f32_e32 v54, v54
	v_rcp_f32_e32 v55, v55
	ds_bpermute_b32 v57, v179, v40
	ds_bpermute_b32 v59, v179, v41
	ds_bpermute_b32 v107, v177, v42
	ds_bpermute_b32 v109, v177, v43
	v_rcp_f32_e32 v50, v50
	v_rcp_f32_e32 v51, v51
	ds_bpermute_b32 v56, v177, v40
	ds_bpermute_b32 v58, v177, v41
	v_pk_mul_f32 v[38:39], v[38:39], v[52:53] op_sel_hi:[1,0]
	v_pk_mul_f32 v[46:47], v[46:47], v[54:55]
	s_waitcnt lgkmcnt(7)
	v_cndmask_b32_e64 v54, v102, v108, s[0:1]
	s_waitcnt lgkmcnt(6)
	v_cndmask_b32_e64 v55, v103, v110, s[0:1]
	v_pk_mul_f32 v[36:37], v[36:37], v[52:53] op_sel_hi:[1,0]
	v_pk_mul_f32 v[44:45], v[44:45], v[50:51]
	v_pk_mul_f32 v[38:39], v[38:39], v[46:47]
	s_waitcnt lgkmcnt(5)
	v_cndmask_b32_e64 v46, v100, v57, s[0:1]
	s_waitcnt lgkmcnt(4)
	v_cndmask_b32_e64 v47, v101, v59, s[0:1]
	s_waitcnt lgkmcnt(3)
	v_cndmask_b32_e32 v50, v82, v107, vcc
	s_waitcnt lgkmcnt(2)
	v_cndmask_b32_e32 v51, v83, v109, vcc
	v_pk_fma_f32 v[54:55], v[94:95], v[54:55], v[98:99]
	v_pk_mul_f32 v[36:37], v[36:37], v[44:45]
	s_waitcnt lgkmcnt(1)
	v_cndmask_b32_e32 v44, v80, v56, vcc
	s_waitcnt lgkmcnt(0)
	v_cndmask_b32_e32 v45, v81, v58, vcc
	v_pk_fma_f32 v[46:47], v[92:93], v[46:47], v[96:97]
	v_pk_fma_f32 v[50:51], v[86:87], v[50:51], v[54:55]
	v_pk_fma_f32 v[44:45], v[84:85], v[44:45], v[46:47]
	v_pk_fma_f32 v[42:43], v[90:91], v[42:43], v[50:51]
	v_pk_fma_f32 v[40:41], v[88:89], v[40:41], v[44:45]
	v_pk_mul_f32 v[44:45], v[42:43], v[42:43]
	v_pk_mul_f32 v[46:47], v[40:41], v[40:41]
	v_fmamk_f32 v44, v44, 0xbdd2d3e8, v216
	v_mul_f32_e32 v44, v42, v44
	v_fmamk_f32 v46, v46, 0xbdd2d3e8, v216
	v_fmamk_f32 v47, v47, 0xbdd2d3e8, v216
	v_exp_f32_e32 v50, v44
	v_fmamk_f32 v44, v45, 0xbdd2d3e8, v216
	v_mul_f32_e32 v46, v40, v46
	v_mul_f32_e32 v47, v41, v47
	v_mul_f32_e32 v44, v43, v44
	v_exp_f32_e32 v46, v46
	v_exp_f32_e32 v47, v47
	v_exp_f32_e32 v51, v44
	v_pk_mul_f32 v[32:33], v[32:33], v[52:53] op_sel_hi:[1,0]
	v_add_f32_e32 v44, 1.0, v46
	v_add_f32_e32 v45, 1.0, v47
	v_add_f32_e32 v46, 1.0, v50
	v_add_f32_e32 v47, 1.0, v51
	v_rcp_f32_e32 v44, v44
	v_rcp_f32_e32 v45, v45
	v_rcp_f32_e32 v46, v46
	v_rcp_f32_e32 v47, v47
	v_pk_mul_f32 v[34:35], v[34:35], v[52:53] op_sel_hi:[1,0]
	v_pk_mul_f32 v[40:41], v[40:41], v[44:45]
	v_pk_mul_f32 v[42:43], v[42:43], v[46:47]
	s_nop 0
	v_pk_mul_f32 v[42:43], v[34:35], v[42:43]
	v_pk_mul_f32 v[34:35], v[32:33], v[40:41]
	v_cvt_pk_bf16_f32 v32, v36, v37
	v_fmamk_f32 v36, v183, 0x3a000000, v215
	v_rsq_f32_e32 v44, v36
	v_cvt_pk_bf16_f32 v33, v38, v39
	v_cvt_pk_bf16_f32 v34, v34, v35
	v_cvt_pk_bf16_f32 v35, v42, v43
	v_mov_b64_e32 v[42:43], s[10:11]
	v_mad_i64_i32 v[36:37], s[6:7], v180, s66, v[42:43]
	v_lshl_add_u64 v[36:37], v[36:37], 0, v[128:129]
	global_store_dwordx4 v[36:37], v[32:35], off nt
	v_pk_mul_f32 v[36:37], v[30:31], v[44:45] op_sel_hi:[1,0]
	v_pk_mul_f32 v[38:39], v[28:29], v[44:45] op_sel_hi:[1,0]
	ds_bpermute_b32 v28, v177, v38
	ds_bpermute_b32 v34, v179, v36
	ds_bpermute_b32 v35, v179, v37
	ds_bpermute_b32 v32, v179, v38
	ds_bpermute_b32 v33, v179, v39
	ds_bpermute_b32 v30, v177, v36
	ds_bpermute_b32 v31, v177, v37
	ds_bpermute_b32 v29, v177, v39
	s_waitcnt lgkmcnt(7)
	v_cndmask_b32_e32 v40, v53, v28, vcc
	s_waitcnt lgkmcnt(6)
	v_cndmask_b32_e64 v52, v104, v34, s[0:1]
	s_waitcnt lgkmcnt(5)
	v_cndmask_b32_e64 v53, v106, v35, s[0:1]
	s_waitcnt lgkmcnt(4)
	v_cndmask_b32_e64 v46, v60, v32, s[0:1]
	s_waitcnt lgkmcnt(3)
	v_cndmask_b32_e64 v47, v62, v33, s[0:1]
	s_waitcnt lgkmcnt(2)
	v_cndmask_b32_e32 v50, v63, v30, vcc
	s_waitcnt lgkmcnt(1)
	v_cndmask_b32_e32 v51, v105, v31, vcc
	v_pk_fma_f32 v[52:53], v[74:75], v[52:53], v[78:79]
	s_waitcnt lgkmcnt(0)
	v_cndmask_b32_e32 v41, v61, v29, vcc
	v_pk_fma_f32 v[46:47], v[72:73], v[46:47], v[76:77]
	v_pk_fma_f32 v[50:51], v[66:67], v[50:51], v[52:53]
	v_pk_fma_f32 v[40:41], v[64:65], v[40:41], v[46:47]
	v_pk_fma_f32 v[36:37], v[70:71], v[36:37], v[50:51]
	v_pk_fma_f32 v[38:39], v[68:69], v[38:39], v[40:41]
	v_pk_mul_f32 v[40:41], v[36:37], v[36:37]
	v_pk_mul_f32 v[46:47], v[38:39], v[38:39]
	v_fmamk_f32 v40, v40, 0xbdd2d3e8, v216
	v_fmamk_f32 v45, v46, 0xbdd2d3e8, v216
	v_mul_f32_e32 v40, v36, v40
	v_mul_f32_e32 v45, v38, v45
	v_fmamk_f32 v46, v47, 0xbdd2d3e8, v216
	v_exp_f32_e32 v47, v40
	v_fmamk_f32 v40, v41, 0xbdd2d3e8, v216
	v_exp_f32_e32 v45, v45
	v_mul_f32_e32 v46, v39, v46
	v_mul_f32_e32 v40, v37, v40
	v_exp_f32_e32 v46, v46
	v_exp_f32_e32 v50, v40
	v_add_f32_e32 v40, 1.0, v45
	v_add_f32_e32 v45, 1.0, v47
	v_add_f32_e32 v41, 1.0, v46
	v_rcp_f32_e32 v46, v45
	v_add_f32_e32 v45, 1.0, v50
	v_rcp_f32_e32 v47, v45
	v_rcp_f32_e32 v40, v40
	v_rcp_f32_e32 v41, v41
	v_pk_mul_f32 v[22:23], v[22:23], v[44:45] op_sel_hi:[1,0]
	v_pk_mul_f32 v[36:37], v[36:37], v[46:47]
	v_pk_mul_f32 v[52:53], v[24:25], v[44:45] op_sel_hi:[1,0]
	v_pk_mul_f32 v[46:47], v[22:23], v[36:37]
	v_pk_mul_f32 v[50:51], v[26:27], v[44:45] op_sel_hi:[1,0]
	ds_bpermute_b32 v22, v177, v52
	ds_bpermute_b32 v26, v179, v52
	ds_bpermute_b32 v36, v179, v53
	v_pk_mul_f32 v[20:21], v[20:21], v[44:45] op_sel_hi:[1,0]
	v_pk_mul_f32 v[38:39], v[38:39], v[40:41]
	ds_bpermute_b32 v23, v177, v53
	v_pk_mul_f32 v[20:21], v[20:21], v[38:39]
	ds_bpermute_b32 v38, v179, v50
	ds_bpermute_b32 v40, v179, v51
	ds_bpermute_b32 v24, v177, v50
	ds_bpermute_b32 v25, v177, v51
	s_waitcnt lgkmcnt(7)
; __device__ __forceinline__ unsigned cvt_pk_bf16(float lo, float hi) { unsigned r; asm volatile("v_cvt_pk_bf16_f32 %0, %1, %2" : "=v"(r) : "v"(lo), "v"(hi)); return r; }
;     __device__ __forceinline__ void operator()(EPI_ARGS) const {
;     ...
;             for (int m = 0; m < 4; ++m) {
;                 const int row = ROW_OF(ai, m);
;                 const float rs = __builtin_amdgcn_rsqf(rsv[ai][m] * (1.0f / D) + EPS);
;                 f32x4 o[2];
; #pragma unroll
;                 for (int n = 0; n < 2; ++n) {
;                     const f32x4 gv = acc[ai][0][m][n] * rs, vv = acc[ai][1][m][n] * rs;
;                     f32x4 r1, r2;
; #pragma unroll
;                     for (int j = 0; j < 4; ++j) { r1[j] = __shfl(gv[j], src1); r2[j] = __shfl(gv[j], src2); }
;                     f32x4 p1, p2;
; #pragma unroll
;                     for (int j = 0; j < 4; ++j) { p1[j] = fr >= 1 ? r1[j] : q1[n][j]; p2[j] = fr >= 2 ? r2[j] : q2[n][j]; }
;                     q1[n] = r1; q2[n] = r2;
;                     const f32x4 cv = bb[n] + w0[n] * p2 + w1[n] * p1 + w2[n] * gv;
;                     o[n] = gelu4(cv) * vv;
;                     if (m == 0 && fr < 2) { const size_t so = ((size_t)blk * 2 + fr) * FF + f0 + 4 * n; *(f32x4*)(headg + so) = gv; *(f32x4*)(headv + so) = vv; }
;                     if (m == 3 && fr >= 14) { const size_t so = ((size_t)blk * 2 + (fr - 14)) * FF + f0 + 4 * n; *(f32x4*)(tailg + so) = gv; }
;                 }
;                 if (!(m == 0 && fr < 2)) {
;                     u32x4 w; w.x = cvt_pk_bf16(o[0][0], o[0][1]); w.y = cvt_pk_bf16(o[0][2], o[0][3]); w.z = cvt_pk_bf16(o[1][0], o[1][1]); w.w = cvt_pk_bf16(o[1][2], o[1][3]);
;                     *(u32x4*)(act + (size_t)row * FF + f0) = w;
	v_cndmask_b32_e32 v54, v56, v22, vcc
	s_waitcnt lgkmcnt(6)
	v_cndmask_b32_e64 v56, v57, v26, s[0:1]
	s_waitcnt lgkmcnt(5)
	v_cndmask_b32_e64 v57, v59, v36, s[0:1]
	s_waitcnt lgkmcnt(4)
	v_cndmask_b32_e32 v55, v58, v23, vcc
	v_pk_fma_f32 v[56:57], v[92:93], v[56:57], v[96:97]
	s_waitcnt lgkmcnt(3)
	v_cndmask_b32_e64 v60, v108, v38, s[0:1]
	s_waitcnt lgkmcnt(2)
	v_cndmask_b32_e64 v61, v110, v40, s[0:1]
	v_pk_fma_f32 v[54:55], v[84:85], v[54:55], v[56:57]
	s_waitcnt lgkmcnt(1)
	v_cndmask_b32_e32 v58, v107, v24, vcc
	s_waitcnt lgkmcnt(0)
	v_cndmask_b32_e32 v59, v109, v25, vcc
	v_pk_fma_f32 v[60:61], v[94:95], v[60:61], v[98:99]
	v_pk_fma_f32 v[52:53], v[88:89], v[52:53], v[54:55]
	v_pk_fma_f32 v[58:59], v[86:87], v[58:59], v[60:61]
	v_pk_mul_f32 v[56:57], v[52:53], v[52:53]
	v_pk_fma_f32 v[50:51], v[90:91], v[50:51], v[58:59]
	v_fmamk_f32 v27, v56, 0xbdd2d3e8, v216
	v_pk_mul_f32 v[54:55], v[50:51], v[50:51]
	v_mul_f32_e32 v27, v52, v27
	v_fmamk_f32 v37, v57, 0xbdd2d3e8, v216
	v_exp_f32_e32 v27, v27
	v_mul_f32_e32 v37, v53, v37
	v_fmamk_f32 v39, v54, 0xbdd2d3e8, v216
	v_exp_f32_e32 v37, v37
	v_mul_f32_e32 v39, v50, v39
	v_fmamk_f32 v41, v55, 0xbdd2d3e8, v216
	v_exp_f32_e32 v39, v39
	v_mul_f32_e32 v41, v51, v41
	v_exp_f32_e32 v41, v41
	v_add_f32_e32 v27, 1.0, v27
	v_rcp_f32_e32 v54, v27
	v_add_f32_e32 v27, 1.0, v37
	v_rcp_f32_e32 v55, v27
	v_add_f32_e32 v27, 1.0, v39
	v_rcp_f32_e32 v56, v27
	v_add_f32_e32 v27, 1.0, v41
	v_rcp_f32_e32 v57, v27
	v_pk_mul_f32 v[16:17], v[16:17], v[44:45] op_sel_hi:[1,0]
	v_pk_mul_f32 v[18:19], v[18:19], v[44:45] op_sel_hi:[1,0]
	v_pk_mul_f32 v[44:45], v[52:53], v[54:55]
	v_pk_mul_f32 v[50:51], v[50:51], v[56:57]
	v_pk_mul_f32 v[16:17], v[16:17], v[44:45]
	v_pk_mul_f32 v[50:51], v[18:19], v[50:51]
	v_cvt_pk_bf16_f32 v18, v20, v21
	v_cvt_pk_bf16_f32 v19, v46, v47
	v_cvt_pk_bf16_f32 v20, v16, v17
	v_fmamk_f32 v16, v181, 0x3a000000, v215
	v_rsq_f32_e32 v16, v16
	v_mad_i64_i32 v[46:47], s[6:7], v178, s66, v[42:43]
	v_lshl_add_u64 v[46:47], v[46:47], 0, v[128:129]
	v_pk_mul_f32 v[14:15], v[14:15], v[16:17] op_sel_hi:[1,0]
	v_pk_mul_f32 v[12:13], v[12:13], v[16:17] op_sel_hi:[1,0]
	ds_bpermute_b32 v27, v177, v12
	ds_bpermute_b32 v42, v179, v12
	ds_bpermute_b32 v37, v177, v13
	ds_bpermute_b32 v43, v179, v13
	ds_bpermute_b32 v39, v177, v14
	ds_bpermute_b32 v44, v179, v14
	ds_bpermute_b32 v41, v177, v15
	ds_bpermute_b32 v45, v179, v15
	v_cvt_pk_bf16_f32 v21, v50, v51
	global_store_dwordx4 v[46:47], v[18:21], off nt
	s_nop 1
	v_lshl_add_u64 v[18:19], s[40:41], 0, v[48:49]
	v_lshl_add_u64 v[20:21], v[174:175], 2, v[18:19]
	s_and_saveexec_b64 s[6:7], s[4:5]
	s_cbranch_execz .LBB0_944
	global_store_dwordx4 v[20:21], v[12:15], off nt
.LBB0_944:
	s_or_b64 exec, exec, s[6:7]
	v_mov_b32_e32 v17, v16
	v_mov_b32_e32 v18, v16
	v_mov_b32_e32 v19, v16
	v_pk_mul_f32 v[10:11], v[10:11], v[18:19]
	v_pk_mul_f32 v[8:9], v[8:9], v[16:17]
	ds_bpermute_b32 v46, v177, v8
	ds_bpermute_b32 v50, v179, v8
	ds_bpermute_b32 v47, v177, v9
	ds_bpermute_b32 v51, v179, v9
	ds_bpermute_b32 v48, v177, v10
	ds_bpermute_b32 v52, v179, v10
	ds_bpermute_b32 v49, v177, v11
	ds_bpermute_b32 v53, v179, v11
	s_and_saveexec_b64 s[6:7], s[4:5]
	s_cbranch_execz .LBB0_946
	global_store_dwordx4 v[20:21], v[8:11], off offset:16 nt
.LBB0_946:
	s_or_b64 exec, exec, s[6:7]
	s_waitcnt lgkmcnt(6)
	v_cndmask_b32_e64 v20, v26, v50, s[0:1]
	s_waitcnt lgkmcnt(4)
	v_cndmask_b32_e64 v21, v36, v51, s[0:1]
	s_waitcnt lgkmcnt(2)
	v_cndmask_b32_e64 v50, v38, v52, s[0:1]
	s_waitcnt lgkmcnt(0)
	v_cndmask_b32_e64 v51, v40, v53, s[0:1]
	v_pk_fma_f32 v[50:51], v[94:95], v[50:51], v[98:99]
	v_pk_fma_f32 v[20:21], v[92:93], v[20:21], v[96:97]
	v_cndmask_b32_e32 v22, v22, v46, vcc
	v_cndmask_b32_e32 v23, v23, v47, vcc
	v_cndmask_b32_e32 v24, v24, v48, vcc
	v_cndmask_b32_e32 v25, v25, v49, vcc
	v_pk_fma_f32 v[20:21], v[84:85], v[22:23], v[20:21]
	v_pk_fma_f32 v[22:23], v[86:87], v[24:25], v[50:51]
	v_pk_fma_f32 v[8:9], v[88:89], v[8:9], v[20:21]
	v_pk_fma_f32 v[10:11], v[90:91], v[10:11], v[22:23]
	v_pk_mul_f32 v[20:21], v[8:9], v[8:9]
	v_pk_mul_f32 v[22:23], v[10:11], v[10:11]
	v_fmamk_f32 v20, v20, 0xbdd2d3e8, v216
	v_fmamk_f32 v21, v21, 0xbdd2d3e8, v216
	v_fmamk_f32 v22, v22, 0xbdd2d3e8, v216
	v_fmamk_f32 v23, v23, 0xbdd2d3e8, v216
	v_mul_f32_e32 v20, v8, v20
	v_mul_f32_e32 v21, v9, v21
	v_mul_f32_e32 v22, v10, v22
	v_mul_f32_e32 v23, v11, v23
	v_exp_f32_e32 v20, v20
	v_exp_f32_e32 v21, v21
	v_exp_f32_e32 v22, v22
	v_exp_f32_e32 v23, v23
	v_add_f32_e32 v20, 1.0, v20
	v_add_f32_e32 v21, 1.0, v21
	v_add_f32_e32 v22, 1.0, v22
	v_add_f32_e32 v23, 1.0, v23
	v_rcp_f32_e32 v20, v20
	v_rcp_f32_e32 v22, v22
	v_rcp_f32_e32 v23, v23
	v_rcp_f32_e32 v21, v21
	v_pk_mul_f32 v[6:7], v[6:7], v[18:19]
	v_pk_mul_f32 v[4:5], v[4:5], v[16:17]
	v_pk_mul_f32 v[10:11], v[10:11], v[22:23]
	v_pk_mul_f32 v[8:9], v[8:9], v[20:21]
	v_pk_mul_f32 v[6:7], v[6:7], v[10:11]
	v_pk_mul_f32 v[4:5], v[4:5], v[8:9]
	v_cndmask_b32_e64 v8, v32, v42, s[0:1]
	v_cndmask_b32_e64 v9, v33, v43, s[0:1]
	v_cndmask_b32_e64 v10, v34, v44, s[0:1]
	v_cndmask_b32_e64 v11, v35, v45, s[0:1]
	v_pk_fma_f32 v[10:11], v[74:75], v[10:11], v[78:79]
	v_pk_fma_f32 v[8:9], v[72:73], v[8:9], v[76:77]
	v_cndmask_b32_e32 v20, v28, v27, vcc
	v_cndmask_b32_e32 v21, v29, v37, vcc
	v_cndmask_b32_e32 v22, v30, v39, vcc
	v_cndmask_b32_e32 v23, v31, v41, vcc
	v_pk_fma_f32 v[8:9], v[64:65], v[20:21], v[8:9]
	v_pk_fma_f32 v[10:11], v[66:67], v[22:23], v[10:11]
	v_pk_fma_f32 v[8:9], v[68:69], v[12:13], v[8:9]
	v_pk_fma_f32 v[10:11], v[70:71], v[14:15], v[10:11]
	v_pk_mul_f32 v[12:13], v[8:9], v[8:9]
	v_pk_mul_f32 v[14:15], v[10:11], v[10:11]
	v_fmamk_f32 v12, v12, 0xbdd2d3e8, v216
	v_fmamk_f32 v13, v13, 0xbdd2d3e8, v216
	v_fmamk_f32 v14, v14, 0xbdd2d3e8, v216
	v_fmamk_f32 v15, v15, 0xbdd2d3e8, v216
	v_mul_f32_e32 v12, v8, v12
	v_mul_f32_e32 v13, v9, v13
	v_mul_f32_e32 v14, v10, v14
	v_mul_f32_e32 v15, v11, v15
	v_exp_f32_e32 v12, v12
	v_exp_f32_e32 v13, v13
	v_exp_f32_e32 v14, v14
	v_exp_f32_e32 v15, v15
	v_add_f32_e32 v12, 1.0, v12
	v_add_f32_e32 v13, 1.0, v13
	v_add_f32_e32 v14, 1.0, v14
	v_add_f32_e32 v15, 1.0, v15
	v_rcp_f32_e32 v12, v12
	v_rcp_f32_e32 v14, v14
	v_rcp_f32_e32 v15, v15
	v_rcp_f32_e32 v13, v13
	v_pk_mul_f32 v[2:3], v[2:3], v[18:19]
	v_pk_mul_f32 v[0:1], v[0:1], v[16:17]
	v_pk_mul_f32 v[10:11], v[10:11], v[14:15]
	v_pk_mul_f32 v[8:9], v[8:9], v[12:13]
	v_pk_mul_f32 v[2:3], v[2:3], v[10:11]
	v_pk_mul_f32 v[0:1], v[0:1], v[8:9]
	s_cmp_eq_u32 s31, 11
	v_cvt_pk_bf16_f32 v0, v0, v1
	v_cvt_pk_bf16_f32 v1, v2, v3
	v_cvt_pk_bf16_f32 v2, v4, v5
	v_mov_b64_e32 v[4:5], s[10:11]
	v_mad_i64_i32 v[4:5], s[0:1], v176, s66, v[4:5]
	v_lshl_add_u64 v[4:5], v[174:175], 1, v[4:5]
	s_mov_b64 s[0:1], -1
	v_cvt_pk_bf16_f32 v3, v6, v7
	global_store_dwordx4 v[4:5], v[0:3], off nt
	s_cbranch_scc1 .LBB0_919
	s_andn2_b64 vcc, exec, s[42:43]
	s_cbranch_vccnz .LBB0_918
	s_barrier
	s_branch .LBB0_918
